# aligned combo12 with background-conversion start delay 2x80 instead of 2x64
# speedup vs baseline: 1.0023x; 1.0023x over previous
; #define LAS __attribute__((address_space(3)))
; __device__ __forceinline__ void cv_background(Frame& F, const CvPtrs& P, int s) {
;     int tv = threadIdx.x; asm volatile("" : "+v"(tv));
;     const int w = __builtin_amdgcn_readfirstlane(tv >> 6) - 1, lane = tv & 63, nbw = F.G * (NWAVES - 1);
;     LAS float* scr = (LAS float*)(F.lds + RING_OFF + (w + 1) * 16384);
;     const int sh_ = cv_bg_share(s), hi = (sh_ + 1) * CV_BG_PER < CV_BG_TOTAL ? (sh_ + 1) * CV_BG_PER : CV_BG_TOTAL;
;     for (int j = sh_ * CV_BG_PER + F.vcu * (NWAVES - 1) + w; j < hi; j += nbw) {
; __device__ __forceinline__ void xcd_barrier_cv(const XcdBarrier& b, Frame& F, const CvPtrs& P, int s, bool local) {
;     asm volatile("s_waitcnt vmcnt(0)" ::: "memory");
;     __syncthreads();
;     if (threadIdx.x < 64) { if (threadIdx.x == 0) { if (local) xcc_barrier_thread0(b); else xcd_barrier_thread0(b); } }
;     else if (cv_bg_share(s) >= 0 && cv_bg_share(s) < CV_BG_SHARES) cv_background(F, P, s);
.LBB0_769:
	s_and_b64 vcc, exec, s[0:1]
	s_cbranch_vccz .LBB0_1015
	s_sleep 80
	s_sleep 80
	v_mov_b32_e32 v4, v0
	s_mov_b64 s[6:7], -1
	v_readfirstlane_b32 s8, v4
	s_mov_b64 s[0:1], 0
	s_cmp_lt_i32 s89, 5
	s_mov_b64 s[4:5], 0
	s_cbranch_scc1 .LBB0_787
	s_cmp_gt_i32 s89, 7
	s_cbranch_scc0 .LBB0_779
	s_cmp_gt_i32 s89, 8
	s_cbranch_scc0 .LBB0_776
	s_cmp_eq_u32 s89, 9
	s_mov_b64 s[4:5], -1
	s_cbranch_scc0 .LBB0_775
	s_mov_b64 s[4:5], 0
